# v4 plus redundant canonicalize v_max removed from idx_scores and DSA attention loops
# speedup vs baseline: 1.0814x; 1.0023x over previous
.LBB0_940:
	s_add_i32 s7, s5, 0xffff8000
	s_and_b32 s7, s7, 0x8000
	v_add_u32_e32 v139, s7, v131
	ds_read_b128 v[66:69], v139
	ds_read_b128 v[82:85], v139 offset:1024
	s_add_i32 s6, s6, 16
	s_add_i32 s5, s5, 0x8000
	s_add_i32 s8, s8, 1
	s_waitcnt lgkmcnt(0)
	v_mfma_f32_32x32x16_bf16 v[66:81], v[66:69], v[122:125], 0
	s_cmp_eq_u32 s3, s8
	v_mfma_f32_32x32x16_bf16 v[66:81], v[82:85], v[98:101], v[66:81]
	ds_read_b128 v[82:85], v139 offset:2048
	ds_read_b128 v[86:89], v139 offset:3072
	s_waitcnt lgkmcnt(0)
	v_mfma_f32_32x32x16_bf16 v[66:81], v[82:85], v[102:105], v[66:81]
	v_mfma_f32_32x32x16_bf16 v[66:81], v[86:89], v[106:109], v[66:81]
	ds_read_b128 v[82:85], v139 offset:4096
	ds_read_b128 v[86:89], v139 offset:5120
	s_waitcnt lgkmcnt(0)
	v_mfma_f32_32x32x16_bf16 v[66:81], v[82:85], v[110:113], v[66:81]
	v_mfma_f32_32x32x16_bf16 v[66:81], v[86:89], v[114:117], v[66:81]
	ds_read_b128 v[82:85], v139 offset:6144
	ds_read_b128 v[86:89], v139 offset:7168
	s_waitcnt lgkmcnt(0)
	v_mfma_f32_32x32x16_bf16 v[66:81], v[82:85], v[118:121], v[66:81]
	ds_read_b128 v[82:85], v139 offset:8192
	ds_read_b128 v[140:143], v139 offset:9216
	v_mfma_f32_32x32x16_bf16 v[66:81], v[86:89], v[126:129], v[66:81]
	s_waitcnt lgkmcnt(0)
	v_mfma_f32_32x32x16_bf16 v[82:97], v[82:85], v[122:125], 0
	s_nop 9
	v_min_f32_e32 v66, 0x42700000, v66
	v_exp_f32_e32 v66, v66
	v_min_f32_e32 v74, 0x42700000, v74
	v_min_f32_e32 v75, 0x42700000, v75
	v_mfma_f32_32x32x16_bf16 v[82:97], v[140:143], v[98:101], v[82:97]
	ds_read_b128 v[140:143], v139 offset:10240
	ds_read_b128 v[144:147], v139 offset:11264
	v_exp_f32_e32 v74, v74
	v_min_f32_e32 v76, 0x42700000, v76
	v_min_f32_e32 v77, 0x42700000, v77
	v_exp_f32_e32 v76, v76
	s_waitcnt lgkmcnt(0)
	v_mfma_f32_32x32x16_bf16 v[82:97], v[140:143], v[102:105], v[82:97]
	v_min_f32_e32 v78, 0x42700000, v78
	v_min_f32_e32 v79, 0x42700000, v79
	v_exp_f32_e32 v78, v78
	v_mfma_f32_32x32x16_bf16 v[82:97], v[144:147], v[106:109], v[82:97]
	ds_read_b128 v[140:143], v139 offset:12288
	ds_read_b128 v[144:147], v139 offset:13312
	v_min_f32_e32 v80, 0x42700000, v80
	v_min_f32_e32 v81, 0x42700000, v81
	v_exp_f32_e32 v80, v80
	s_waitcnt lgkmcnt(0)
	v_mfma_f32_32x32x16_bf16 v[82:97], v[140:143], v[110:113], v[82:97]
	v_mfma_f32_32x32x16_bf16 v[82:97], v[144:147], v[114:117], v[82:97]
	ds_read_b128 v[140:143], v139 offset:14336
	ds_read_b128 v[144:147], v139 offset:15360
	ds_read_b128 v[148:151], v139 offset:20480
	ds_read_b128 v[156:159], v139 offset:24576
	ds_read_b128 v[160:163], v139 offset:25600
	s_waitcnt lgkmcnt(0)
	v_mfma_f32_32x32x16_bf16 v[82:97], v[140:143], v[118:121], v[82:97]
	global_load_dwordx2 v[140:141], v[136:137], off offset:-4
	v_lshl_add_u64 v[136:137], v[136:137], 0, 8
	s_waitcnt vmcnt(0)
	v_lshrrev_b32_e32 v140, v130, v140
	v_mfma_f32_32x32x16_bf16 v[82:97], v[144:147], v[126:129], v[82:97]
	v_and_b32_e32 v142, 1, v140
	v_lshrrev_b32_e32 v141, v130, v141
	v_cmp_eq_u32_e32 vcc, 1, v142
	s_nop 1
	v_cndmask_b32_e32 v168, 0, v66, vcc
	v_and_b32_e32 v66, 1, v141
	s_nop 4
	v_min_f32_e32 v82, 0x42700000, v82
	v_exp_f32_e32 v82, v82
	v_cmp_eq_u32_e32 vcc, 1, v66
	v_min_f32_e32 v66, 0x42700000, v67
	v_exp_f32_e32 v66, v66
	v_cndmask_b32_e32 v169, 0, v82, vcc
	v_min_f32_e32 v67, 0x42700000, v83
	v_and_b32_e32 v82, 2, v140
	v_cmp_ne_u32_e32 vcc, 0, v82
	v_exp_f32_e32 v67, v67
	v_and_b32_e32 v83, 0x800, v140
	v_cndmask_b32_e32 v170, 0, v66, vcc
	v_and_b32_e32 v66, 2, v141
	v_cmp_ne_u32_e32 vcc, 0, v66
	v_min_f32_e32 v66, 0x42700000, v68
	v_exp_f32_e32 v66, v66
	v_cndmask_b32_e32 v171, 0, v67, vcc
	v_min_f32_e32 v67, 0x42700000, v84
	v_and_b32_e32 v68, 4, v140
	v_exp_f32_e32 v67, v67
	v_cmp_ne_u32_e32 vcc, 0, v68
	v_and_b32_e32 v68, 8, v140
	s_nop 0
	v_cndmask_b32_e32 v172, 0, v66, vcc
	v_and_b32_e32 v66, 4, v141
	v_cmp_ne_u32_e32 vcc, 0, v66
	v_min_f32_e32 v66, 0x42700000, v69
	v_cndmask_b32_e32 v173, 0, v67, vcc
	v_exp_f32_e32 v66, v66
	v_min_f32_e32 v67, 0x42700000, v85
	v_exp_f32_e32 v67, v67
	v_cmp_ne_u32_e32 vcc, 0, v68
	v_and_b32_e32 v85, 0x20000, v140
	s_nop 0
	v_cndmask_b32_e32 v174, 0, v66, vcc
	v_and_b32_e32 v66, 8, v141
	v_cmp_ne_u32_e32 vcc, 0, v66
	v_min_f32_e32 v66, 0x42700000, v70
	v_cndmask_b32_e32 v175, 0, v67, vcc
	v_min_f32_e32 v67, 0x42700000, v86
	v_exp_f32_e32 v68, v67
	v_min_f32_e32 v67, 0x42700000, v71
	v_exp_f32_e32 v66, v66
	v_exp_f32_e32 v69, v67
	v_min_f32_e32 v67, 0x42700000, v87
	v_exp_f32_e32 v70, v67
	v_and_b32_e32 v67, 0x100, v140
	v_and_b32_e32 v71, 0x200, v140
	v_cmp_ne_u32_e32 vcc, 0, v67
	v_and_b32_e32 v87, 0x80000, v140
	s_nop 0
	v_cndmask_b32_e32 v67, 0, v66, vcc
	v_cmp_ne_u32_e32 vcc, 0, v71
	v_and_b32_e32 v71, 0x200, v141
	s_nop 0
	v_cndmask_b32_e32 v66, 0, v69, vcc
	v_and_b32_e32 v69, 0x100, v141
	v_cmp_ne_u32_e32 vcc, 0, v69
	s_nop 1
	v_cndmask_b32_e32 v69, 0, v68, vcc
	v_cmp_ne_u32_e32 vcc, 0, v71
	v_min_f32_e32 v71, 0x42700000, v88
	v_cndmask_b32_e32 v68, 0, v70, vcc
	v_max_f32_e32 v70, v72, v72
	v_exp_f32_e32 v72, v71
	v_min_f32_e32 v71, 0x42700000, v73
	v_min_f32_e32 v70, 0x42700000, v70
	v_exp_f32_e32 v70, v70
	v_exp_f32_e32 v73, v71
	v_min_f32_e32 v71, 0x42700000, v89
	v_exp_f32_e32 v82, v71
	v_and_b32_e32 v71, 0x400, v140
	v_cmp_ne_u32_e32 vcc, 0, v71
	v_and_b32_e32 v89, 0x2000000, v140
	s_nop 0
	v_cndmask_b32_e32 v71, 0, v70, vcc
	v_cmp_ne_u32_e32 vcc, 0, v83
	v_and_b32_e32 v83, 0x800, v141
	s_nop 0
	v_cndmask_b32_e32 v70, 0, v73, vcc
	v_and_b32_e32 v73, 0x400, v141
	v_cmp_ne_u32_e32 vcc, 0, v73
	s_nop 1
	v_cndmask_b32_e32 v73, 0, v72, vcc
	v_cmp_ne_u32_e32 vcc, 0, v83
	v_exp_f32_e32 v83, v75
	v_min_f32_e32 v75, 0x42700000, v91
	v_cndmask_b32_e32 v72, 0, v82, vcc
	v_min_f32_e32 v82, 0x42700000, v90
	v_exp_f32_e32 v84, v75
	v_and_b32_e32 v75, 0x10000, v140
	v_exp_f32_e32 v82, v82
	v_cmp_ne_u32_e32 vcc, 0, v75
	v_and_b32_e32 v91, 0x8000000, v140
	v_pk_mov_b32 v[152:153], v[72:73], v[72:73] op_sel:[1,0]
	v_cndmask_b32_e32 v75, 0, v74, vcc
	v_cmp_ne_u32_e32 vcc, 0, v85
	v_and_b32_e32 v85, 0x20000, v141
	s_nop 0
	v_cndmask_b32_e32 v74, 0, v83, vcc
	v_and_b32_e32 v83, 0x10000, v141
	v_cmp_ne_u32_e32 vcc, 0, v83
	s_nop 1
	v_cndmask_b32_e32 v83, 0, v82, vcc
	v_cmp_ne_u32_e32 vcc, 0, v85
	v_exp_f32_e32 v85, v77
	v_min_f32_e32 v77, 0x42700000, v93
	v_cndmask_b32_e32 v82, 0, v84, vcc
	v_min_f32_e32 v84, 0x42700000, v92
	v_exp_f32_e32 v86, v77
	v_and_b32_e32 v77, 0x40000, v140
	v_exp_f32_e32 v84, v84
	v_cmp_ne_u32_e32 vcc, 0, v77
	v_pk_mov_b32 v[92:93], v[66:67], v[66:67] op_sel:[1,0]
	v_pk_add_f32 v[66:67], v[66:67], v[68:69]
	v_cndmask_b32_e32 v77, 0, v76, vcc
	v_cmp_ne_u32_e32 vcc, 0, v87
	v_and_b32_e32 v87, 0x80000, v141
	v_cvt_pk_bf16_f32 v92, v92, v93
	v_cndmask_b32_e32 v76, 0, v85, vcc
	v_and_b32_e32 v85, 0x40000, v141
	v_cmp_ne_u32_e32 vcc, 0, v85
	s_nop 1
	v_cndmask_b32_e32 v85, 0, v84, vcc
	v_cmp_ne_u32_e32 vcc, 0, v87
	v_exp_f32_e32 v87, v79
	v_min_f32_e32 v79, 0x42700000, v95
	v_cndmask_b32_e32 v84, 0, v86, vcc
	v_min_f32_e32 v86, 0x42700000, v94
	v_exp_f32_e32 v88, v79
	v_and_b32_e32 v79, 0x1000000, v140
	v_exp_f32_e32 v86, v86
	v_cmp_ne_u32_e32 vcc, 0, v79
	v_pk_mov_b32 v[94:95], v[70:71], v[70:71] op_sel:[1,0]
	s_nop 0
	v_cndmask_b32_e32 v79, 0, v78, vcc
	v_cmp_ne_u32_e32 vcc, 0, v89
	v_and_b32_e32 v89, 0x2000000, v141
	v_cvt_pk_bf16_f32 v93, v94, v95
	v_cndmask_b32_e32 v78, 0, v87, vcc
	v_and_b32_e32 v87, 0x1000000, v141
	v_cmp_ne_u32_e32 vcc, 0, v87
	v_pk_mov_b32 v[94:95], v[74:75], v[74:75] op_sel:[1,0]
	s_nop 0
	v_cndmask_b32_e32 v87, 0, v86, vcc
	v_cmp_ne_u32_e32 vcc, 0, v89
	v_exp_f32_e32 v89, v81
	v_min_f32_e32 v81, 0x42700000, v97
	v_cndmask_b32_e32 v86, 0, v88, vcc
	v_min_f32_e32 v88, 0x42700000, v96
	v_exp_f32_e32 v90, v81
	v_and_b32_e32 v81, 0x4000000, v140
	v_exp_f32_e32 v88, v88
	v_cmp_ne_u32_e32 vcc, 0, v81
	v_pk_mov_b32 v[96:97], v[76:77], v[76:77] op_sel:[1,0]
	v_cvt_pk_bf16_f32 v94, v94, v95
	v_cndmask_b32_e32 v81, 0, v80, vcc
	v_cmp_ne_u32_e32 vcc, 0, v91
	v_and_b32_e32 v91, 0x8000000, v141
	v_cvt_pk_bf16_f32 v95, v96, v97
	v_cndmask_b32_e32 v80, 0, v89, vcc
	v_and_b32_e32 v89, 0x4000000, v141
	v_cmp_ne_u32_e32 vcc, 0, v89
	ds_read_b128 v[140:143], v139 offset:16384
	v_pk_mov_b32 v[96:97], v[78:79], v[78:79] op_sel:[1,0]
	v_cndmask_b32_e32 v89, 0, v88, vcc
	v_cmp_ne_u32_e32 vcc, 0, v91
	v_cvt_pk_bf16_f32 v91, v172, v174
	v_pk_mov_b32 v[144:145], v[80:81], v[80:81] op_sel:[1,0]
	v_cndmask_b32_e32 v88, 0, v90, vcc
	v_cvt_pk_bf16_f32 v90, v168, v170
	v_cvt_pk_bf16_f32 v96, v96, v97
	v_cvt_pk_bf16_f32 v97, v144, v145
	ds_read_b128 v[144:147], v139 offset:17408
	s_waitcnt lgkmcnt(1)
	v_mfma_f32_32x32x16_bf16 v[2:17], v[90:93], v[140:143], v[2:17]
	v_pk_mov_b32 v[142:143], v[68:69], v[68:69] op_sel:[1,0]
	v_cvt_pk_bf16_f32 v140, v169, v171
	v_cvt_pk_bf16_f32 v142, v142, v143
	v_cvt_pk_bf16_f32 v143, v152, v153
	ds_read_b128 v[152:155], v139 offset:21504
	v_cvt_pk_bf16_f32 v141, v173, v175
	v_pk_add_f32 v[68:69], v[70:71], v[72:73]
	v_mfma_f32_32x32x16_bf16 v[2:17], v[94:97], v[148:151], v[2:17]
	v_pk_mov_b32 v[148:149], v[82:83], v[82:83] op_sel:[1,0]
	v_pk_mov_b32 v[150:151], v[84:85], v[84:85] op_sel:[1,0]
	v_cvt_pk_bf16_f32 v148, v148, v149
	v_cvt_pk_bf16_f32 v149, v150, v151
	v_pk_mov_b32 v[150:151], v[86:87], v[86:87] op_sel:[1,0]
	v_pk_add_f32 v[70:71], v[74:75], v[82:83]
	v_cvt_pk_bf16_f32 v150, v150, v151
	s_waitcnt lgkmcnt(1)
	v_mfma_f32_32x32x16_bf16 v[18:33], v[90:93], v[144:147], v[18:33]
	v_add_f32_e64 v74, v78, v86
	v_add_f32_e64 v75, v79, v87
	v_add_f32_e64 v72, v76, v84
	v_add_f32_e64 v73, v77, v85
	v_add_f32_e64 v76, v80, v88
	v_add_f32_e64 v77, v81, v89
	v_mfma_f32_32x32x16_bf16 v[2:17], v[140:143], v[156:159], v[2:17]
	v_pk_mov_b32 v[156:157], v[88:89], v[88:89] op_sel:[1,0]
	s_nop 0
	v_cvt_pk_bf16_f32 v151, v156, v157
	ds_read_b128 v[156:159], v139 offset:28672
	ds_read_b128 v[164:167], v139 offset:29696
	s_waitcnt lgkmcnt(2)
	v_mfma_f32_32x32x16_bf16 v[18:33], v[94:97], v[152:155], v[18:33]
	ds_read_b128 v[144:147], v139 offset:18432
	ds_read_b128 v[152:155], v139 offset:19456
	s_waitcnt lgkmcnt(1)
	v_mfma_f32_32x32x16_bf16 v[34:49], v[90:93], v[144:147], v[34:49]
	v_mfma_f32_32x32x16_bf16 v[2:17], v[148:151], v[156:159], v[2:17]
	ds_read_b128 v[144:147], v139 offset:22528
	ds_read_b128 v[156:159], v139 offset:23552
	s_waitcnt lgkmcnt(1)
	v_mfma_f32_32x32x16_bf16 v[34:49], v[94:97], v[144:147], v[34:49]
	v_mfma_f32_32x32x16_bf16 v[50:65], v[90:93], v[152:155], v[50:65]
	v_mfma_f32_32x32x16_bf16 v[18:33], v[140:143], v[160:163], v[18:33]
	ds_read_b128 v[144:147], v139 offset:26624
	ds_read_b128 v[160:163], v139 offset:27648
	s_waitcnt lgkmcnt(1)
	v_mfma_f32_32x32x16_bf16 v[34:49], v[140:143], v[144:147], v[34:49]
	v_mfma_f32_32x32x16_bf16 v[50:65], v[94:97], v[156:159], v[50:65]
	v_mfma_f32_32x32x16_bf16 v[18:33], v[148:151], v[164:167], v[18:33]
	ds_read_b128 v[144:147], v139 offset:30720
	ds_read_b128 v[164:167], v139 offset:31744
	v_add_f32_e32 v139, v168, v169
	v_add_f32_e32 v78, v138, v139
	s_waitcnt lgkmcnt(0)
	s_barrier
	v_mfma_f32_32x32x16_bf16 v[34:49], v[148:151], v[144:147], v[34:49]
	v_add_f32_e32 v144, v170, v171
	v_add_f32_e32 v145, v172, v173
	v_add_f32_e32 v78, v144, v78
	v_add_f32_e32 v146, v174, v175
	v_add_f32_e32 v78, v145, v78
	v_add_f32_e32 v78, v146, v78
	v_add_f32_e32 v67, v67, v78
	v_mfma_f32_32x32x16_bf16 v[50:65], v[140:143], v[160:163], v[50:65]
	v_add_f32_e32 v66, v66, v67
	v_add_f32_e32 v66, v69, v66
	v_add_f32_e32 v66, v68, v66
	v_add_f32_e32 v66, v71, v66
	v_add_f32_e32 v66, v70, v66
	v_add_f32_e32 v66, v73, v66
	v_add_f32_e32 v66, v72, v66
	v_mfma_f32_32x32x16_bf16 v[50:65], v[148:151], v[164:167], v[50:65]
	v_add_f32_e32 v66, v75, v66
	v_add_f32_e32 v66, v74, v66
	v_add_f32_e32 v66, v77, v66
	v_add_f32_e32 v138, v76, v66
	s_cbranch_scc1 .LBB0_943

.LBB0_951:
	s_waitcnt vmcnt(4)
	v_mfma_f32_32x32x16_bf16 v[2:17], v[42:45], v[66:69], 0
	s_add_i32 s2, s0, -2
	s_add_i32 s6, s0, -1
	s_cmp_lt_i32 s2, s1
	s_cselect_b32 s6, s6, s1
	s_ashr_i32 s7, s6, 31
	s_lshl_b64 s[6:7], s[6:7], 12
	v_lshl_add_u64 v[18:19], v[98:99], 0, s[6:7]
	s_waitcnt vmcnt(1)
	v_mfma_f32_32x32x16_bf16 v[2:17], v[62:65], v[70:73], v[2:17]
	global_load_dwordx4 v[94:97], v[18:19], off
	global_load_dwordx4 v[90:93], v[18:19], off offset:1024
	global_load_dwordx4 v[86:89], v[18:19], off offset:2048
	global_load_dwordx4 v[82:85], v[18:19], off offset:3072
	v_lshl_add_u64 v[104:105], v[100:101], 0, v[0:1]
	s_cmp_ge_i32 s2, s1
	v_mfma_f32_32x32x16_bf16 v[2:17], v[34:37], v[74:77], v[2:17]
	s_waitcnt vmcnt(4)
	v_mfma_f32_32x32x16_bf16 v[2:17], v[38:41], v[78:81], v[2:17]
	v_mfma_f32_32x32x16_bf16 v[18:33], v[54:57], v[66:69], 0
	s_nop 10
	v_max_f32_e32 v10, 0, v10
	v_max_f32_e32 v2, 0, v2
	v_max_f32_e32 v11, 0, v11
	v_fma_f32 v10, v10, v116, 0
	v_max_f32_e32 v13, v13, v13
	v_max_f32_e32 v3, 0, v3
	v_max_f32_e32 v12, 0, v12
	v_fma_f32 v2, v2, v108, 0
	v_fmac_f32_e32 v10, v11, v117
	v_max_f32_e32 v4, 0, v4
	v_fmac_f32_e32 v2, v3, v109
	v_fmac_f32_e32 v10, v12, v118
	v_max_f32_e32 v3, 0, v13
	v_mfma_f32_32x32x16_bf16 v[18:33], v[46:49], v[70:73], v[18:33]
	v_max_f32_e32 v5, 0, v5
	v_fmac_f32_e32 v2, v4, v110
	v_fmac_f32_e32 v10, v3, v119
	v_max_f32_e32 v3, 0, v6
	v_fmac_f32_e32 v2, v5, v111
	v_fmac_f32_e32 v2, v3, v112
	v_max_f32_e32 v3, 0, v14
	v_fmac_f32_e32 v10, v3, v120
	v_max_f32_e32 v3, 0, v7
	v_fmac_f32_e32 v2, v3, v113
	v_max_f32_e32 v3, 0, v15
	v_mfma_f32_32x32x16_bf16 v[18:33], v[50:53], v[74:77], v[18:33]
	v_fmac_f32_e32 v10, v3, v121
	v_max_f32_e32 v3, 0, v8
	v_fmac_f32_e32 v2, v3, v114
	v_max_f32_e32 v3, 0, v16
	v_fmac_f32_e32 v10, v3, v122
	v_max_f32_e32 v3, 0, v9
	v_fmac_f32_e32 v2, v3, v115
	v_max_f32_e32 v3, 0, v17
	v_mfma_f32_32x32x16_bf16 v[18:33], v[58:61], v[78:81], v[18:33]
	v_fmac_f32_e32 v10, v3, v123
	v_mov_b32_e32 v3, v2
	s_nop 1
	v_permlane32_swap_b32_e32 v2, v3
	v_add_f32_e32 v2, v2, v3
	v_mov_b32_e32 v3, v10
	s_nop 1
	v_permlane32_swap_b32_e32 v10, v3
	v_add_f32_e32 v3, v10, v3
	v_cndmask_b32_e64 v4, v3, v2, s[4:5]
	v_lshl_add_u64 v[2:3], v[102:103], 0, v[0:1]
	v_add_co_u32_e32 v106, vcc, s9, v2
	v_max_f32_e32 v2, 0, v18
	s_nop 0
	v_addc_co_u32_e32 v107, vcc, 0, v3, vcc
	global_store_dword v[106:107], v4, off
	v_max_f32_e32 v4, 0, v19
	v_fma_f32 v2, v2, v124, 0
	v_max_f32_e32 v3, 0, v26
	v_fmac_f32_e32 v2, v4, v125
	v_max_f32_e32 v4, 0, v27
	v_fma_f32 v3, v3, v132, 0
	v_fmac_f32_e32 v3, v4, v133
	v_max_f32_e32 v4, 0, v20
	v_fmac_f32_e32 v2, v4, v126
	v_max_f32_e32 v4, 0, v28
	v_fmac_f32_e32 v3, v4, v134
	v_max_f32_e32 v4, 0, v21
	v_fmac_f32_e32 v2, v4, v127
	v_max_f32_e32 v4, 0, v29
	v_fmac_f32_e32 v3, v4, v135
	v_max_f32_e32 v4, 0, v22
	v_fmac_f32_e32 v2, v4, v128
	v_max_f32_e32 v4, 0, v30
	v_fmac_f32_e32 v3, v4, v136
	v_max_f32_e32 v4, 0, v23
	v_fmac_f32_e32 v2, v4, v129
	v_max_f32_e32 v4, 0, v31
	v_fmac_f32_e32 v3, v4, v137
	v_max_f32_e32 v4, 0, v24
	v_fmac_f32_e32 v2, v4, v130
	v_max_f32_e32 v4, 0, v32
	v_fmac_f32_e32 v3, v4, v138
	v_max_f32_e32 v4, 0, v25
	v_fmac_f32_e32 v2, v4, v131
	v_max_f32_e32 v4, 0, v33
	v_fmac_f32_e32 v3, v4, v139
	v_mov_b32_e32 v4, v2
	s_nop 1
	v_permlane32_swap_b32_e32 v2, v4
	v_add_f32_e32 v2, v2, v4
	v_mov_b32_e32 v4, v3
	s_nop 1
	v_permlane32_swap_b32_e32 v3, v4
	v_add_f32_e32 v3, v3, v4
	v_cndmask_b32_e64 v4, v3, v2, s[4:5]
	v_add_co_u32_e32 v2, vcc, 0x62d00000, v104
	s_nop 1
	v_addc_co_u32_e32 v3, vcc, 0, v105, vcc
	global_store_dword v[2:3], v4, off
	s_cbranch_scc1 .LBB0_950
	s_waitcnt vmcnt(5)
	v_mfma_f32_32x32x16_bf16 v[2:17], v[42:45], v[94:97], 0
	s_min_i32 s6, s0, s1
	s_ashr_i32 s7, s6, 31
	s_lshl_b64 s[6:7], s[6:7], 12
	v_lshl_add_u64 v[18:19], v[98:99], 0, s[6:7]
	global_load_dwordx4 v[66:69], v[18:19], off
	global_load_dwordx4 v[70:73], v[18:19], off offset:1024
	global_load_dwordx4 v[74:77], v[18:19], off offset:2048
	global_load_dwordx4 v[78:81], v[18:19], off offset:3072
	s_waitcnt vmcnt(8)
	v_mfma_f32_32x32x16_bf16 v[2:17], v[62:65], v[90:93], v[2:17]
	s_waitcnt vmcnt(7)
	v_mfma_f32_32x32x16_bf16 v[2:17], v[34:37], v[86:89], v[2:17]
	s_waitcnt vmcnt(6)
	v_mfma_f32_32x32x16_bf16 v[2:17], v[38:41], v[82:85], v[2:17]
	v_mfma_f32_32x32x16_bf16 v[18:33], v[54:57], v[94:97], 0
	s_nop 10
	v_max_f32_e32 v10, 0, v10
	v_max_f32_e32 v2, 0, v2
	v_mfma_f32_32x32x16_bf16 v[18:33], v[46:49], v[90:93], v[18:33]
	v_max_f32_e32 v11, 0, v11
	v_fma_f32 v10, v10, v116, 0
	v_max_f32_e32 v3, 0, v3
	v_max_f32_e32 v12, 0, v12
	v_fma_f32 v2, v2, v108, 0
	v_fmac_f32_e32 v10, v11, v117
	v_max_f32_e32 v4, 0, v4
	v_max_f32_e32 v13, 0, v13
	v_fmac_f32_e32 v2, v3, v109
	v_fmac_f32_e32 v10, v12, v118
	v_max_f32_e32 v3, 0, v14
	v_max_f32_e32 v5, 0, v5
	v_fmac_f32_e32 v2, v4, v110
	v_fmac_f32_e32 v10, v13, v119
	v_max_f32_e32 v6, 0, v6
	v_fmac_f32_e32 v2, v5, v111
	v_fmac_f32_e32 v10, v3, v120
	v_max_f32_e32 v3, 0, v7
	v_fmac_f32_e32 v2, v6, v112
	v_fmac_f32_e32 v2, v3, v113
	v_max_f32_e32 v3, 0, v15
	v_mfma_f32_32x32x16_bf16 v[18:33], v[50:53], v[86:89], v[18:33]
	v_fmac_f32_e32 v10, v3, v121
	v_max_f32_e32 v3, 0, v8
	v_fmac_f32_e32 v2, v3, v114
	v_max_f32_e32 v3, 0, v16
	v_fmac_f32_e32 v10, v3, v122
	v_max_f32_e32 v3, 0, v9
	v_fmac_f32_e32 v2, v3, v115
	v_max_f32_e32 v3, 0, v17
	v_mfma_f32_32x32x16_bf16 v[18:33], v[58:61], v[82:85], v[18:33]
	v_fmac_f32_e32 v10, v3, v123
	v_mov_b32_e32 v3, v2
	s_nop 1
	v_permlane32_swap_b32_e32 v2, v3
	v_add_f32_e32 v2, v2, v3
	v_mov_b32_e32 v3, v10
	s_nop 1
	v_permlane32_swap_b32_e32 v10, v3
	v_add_f32_e32 v3, v10, v3
	v_cndmask_b32_e64 v2, v3, v2, s[4:5]
	global_store_dword v[106:107], v2, off offset:128
	v_max_f32_e32 v2, 0, v18
	v_max_f32_e32 v4, 0, v19
	v_fma_f32 v2, v2, v124, 0
	v_max_f32_e32 v3, 0, v26
	v_fmac_f32_e32 v2, v4, v125
	v_max_f32_e32 v4, 0, v27
	v_fma_f32 v3, v3, v132, 0
	v_fmac_f32_e32 v3, v4, v133
	v_max_f32_e32 v4, 0, v20
	v_fmac_f32_e32 v2, v4, v126
	v_max_f32_e32 v4, 0, v28
	v_fmac_f32_e32 v3, v4, v134
	v_max_f32_e32 v4, 0, v21
	v_fmac_f32_e32 v2, v4, v127
	v_max_f32_e32 v4, 0, v29
	v_fmac_f32_e32 v3, v4, v135
	v_max_f32_e32 v4, 0, v22
	v_fmac_f32_e32 v2, v4, v128
	v_max_f32_e32 v4, 0, v30
	v_fmac_f32_e32 v3, v4, v136
	v_max_f32_e32 v4, 0, v23
	v_fmac_f32_e32 v2, v4, v129
	v_max_f32_e32 v4, 0, v31
	v_fmac_f32_e32 v3, v4, v137
	v_max_f32_e32 v4, 0, v24
	v_fmac_f32_e32 v2, v4, v130
	v_max_f32_e32 v4, 0, v32
	v_fmac_f32_e32 v3, v4, v138
	v_max_f32_e32 v4, 0, v25
	v_fmac_f32_e32 v2, v4, v131
	v_max_f32_e32 v4, 0, v33
	v_fmac_f32_e32 v3, v4, v139
	v_mov_b32_e32 v4, v2
	s_nop 1
	v_permlane32_swap_b32_e32 v2, v4
	v_add_f32_e32 v2, v2, v4
	v_mov_b32_e32 v4, v3
	s_nop 1
	v_permlane32_swap_b32_e32 v3, v4
	v_add_f32_e32 v3, v3, v4
	v_cndmask_b32_e64 v4, v3, v2, s[4:5]
	v_add_co_u32_e32 v2, vcc, s9, v104
	s_nop 1
	v_addc_co_u32_e32 v3, vcc, 0, v105, vcc
	global_store_dword v[2:3], v4, off offset:128
	s_branch .LBB0_950

.LBB0_2572:
	s_waitcnt vmcnt(4)
	v_mfma_f32_32x32x16_bf16 v[2:17], v[42:45], v[66:69], 0
	s_add_i32 s8, s2, -2
	s_add_i32 s6, s2, -1
	s_cmp_lt_i32 s8, s3
	s_cselect_b32 s6, s6, s3
	s_ashr_i32 s7, s6, 31
	s_lshl_b64 s[6:7], s[6:7], 12
	v_lshl_add_u64 v[18:19], v[98:99], 0, s[6:7]
	s_waitcnt vmcnt(1)
	v_mfma_f32_32x32x16_bf16 v[2:17], v[62:65], v[70:73], v[2:17]
	global_load_dwordx4 v[94:97], v[18:19], off
	global_load_dwordx4 v[90:93], v[18:19], off offset:1024
	global_load_dwordx4 v[86:89], v[18:19], off offset:2048
	global_load_dwordx4 v[82:85], v[18:19], off offset:3072
	v_lshl_add_u64 v[104:105], v[100:101], 0, v[0:1]
	s_cmp_ge_i32 s8, s3
	v_mfma_f32_32x32x16_bf16 v[2:17], v[34:37], v[74:77], v[2:17]
	s_waitcnt vmcnt(4)
	v_mfma_f32_32x32x16_bf16 v[2:17], v[38:41], v[78:81], v[2:17]
	v_mfma_f32_32x32x16_bf16 v[18:33], v[54:57], v[66:69], 0
	s_nop 10
	v_max_f32_e32 v10, 0, v10
	v_max_f32_e32 v2, 0, v2
	v_max_f32_e32 v11, 0, v11
	v_fma_f32 v10, v10, v116, 0
	v_max_f32_e32 v13, v13, v13
	v_max_f32_e32 v3, 0, v3
	v_max_f32_e32 v12, 0, v12
	v_fma_f32 v2, v2, v108, 0
	v_fmac_f32_e32 v10, v11, v117
	v_max_f32_e32 v4, 0, v4
	v_fmac_f32_e32 v2, v3, v109
	v_fmac_f32_e32 v10, v12, v118
	v_max_f32_e32 v3, 0, v13
	v_mfma_f32_32x32x16_bf16 v[18:33], v[46:49], v[70:73], v[18:33]
	v_max_f32_e32 v5, 0, v5
	v_fmac_f32_e32 v2, v4, v110
	v_fmac_f32_e32 v10, v3, v119
	v_max_f32_e32 v3, 0, v6
	v_fmac_f32_e32 v2, v5, v111
	v_fmac_f32_e32 v2, v3, v112
	v_max_f32_e32 v3, 0, v14
	v_fmac_f32_e32 v10, v3, v120
	v_max_f32_e32 v3, 0, v7
	v_fmac_f32_e32 v2, v3, v113
	v_max_f32_e32 v3, 0, v15
	v_mfma_f32_32x32x16_bf16 v[18:33], v[50:53], v[74:77], v[18:33]
	v_fmac_f32_e32 v10, v3, v121
	v_max_f32_e32 v3, 0, v8
	v_fmac_f32_e32 v2, v3, v114
	v_max_f32_e32 v3, 0, v16
	v_fmac_f32_e32 v10, v3, v122
	v_max_f32_e32 v3, 0, v9
	v_fmac_f32_e32 v2, v3, v115
	v_max_f32_e32 v3, 0, v17
	v_mfma_f32_32x32x16_bf16 v[18:33], v[58:61], v[78:81], v[18:33]
	v_fmac_f32_e32 v10, v3, v123
	v_mov_b32_e32 v3, v2
	s_nop 1
	v_permlane32_swap_b32_e32 v2, v3
	v_add_f32_e32 v2, v2, v3
	v_mov_b32_e32 v3, v10
	s_nop 1
	v_permlane32_swap_b32_e32 v10, v3
	v_add_f32_e32 v3, v10, v3
	v_cndmask_b32_e64 v4, v3, v2, s[4:5]
	v_lshl_add_u64 v[2:3], v[102:103], 0, v[0:1]
	v_add_co_u32_e32 v106, vcc, s52, v2
	v_max_f32_e32 v2, 0, v18
	s_nop 0
	v_addc_co_u32_e32 v107, vcc, 0, v3, vcc
	global_store_dword v[106:107], v4, off
	v_max_f32_e32 v4, 0, v19
	v_fma_f32 v2, v2, v124, 0
	v_max_f32_e32 v3, 0, v26
	v_fmac_f32_e32 v2, v4, v125
	v_max_f32_e32 v4, 0, v27
	v_fma_f32 v3, v3, v132, 0
	v_fmac_f32_e32 v3, v4, v133
	v_max_f32_e32 v4, 0, v20
	v_fmac_f32_e32 v2, v4, v126
	v_max_f32_e32 v4, 0, v28
	v_fmac_f32_e32 v3, v4, v134
	v_max_f32_e32 v4, 0, v21
	v_fmac_f32_e32 v2, v4, v127
	v_max_f32_e32 v4, 0, v29
	v_fmac_f32_e32 v3, v4, v135
	v_max_f32_e32 v4, 0, v22
	v_fmac_f32_e32 v2, v4, v128
	v_max_f32_e32 v4, 0, v30
	v_fmac_f32_e32 v3, v4, v136
	v_max_f32_e32 v4, 0, v23
	v_fmac_f32_e32 v2, v4, v129
	v_max_f32_e32 v4, 0, v31
	v_fmac_f32_e32 v3, v4, v137
	v_max_f32_e32 v4, 0, v24
	v_fmac_f32_e32 v2, v4, v130
	v_max_f32_e32 v4, 0, v32
	v_fmac_f32_e32 v3, v4, v138
	v_max_f32_e32 v4, 0, v25
	v_fmac_f32_e32 v2, v4, v131
	v_max_f32_e32 v4, 0, v33
	v_fmac_f32_e32 v3, v4, v139
	v_mov_b32_e32 v4, v2
	s_nop 1
	v_permlane32_swap_b32_e32 v2, v4
	v_add_f32_e32 v2, v2, v4
	v_mov_b32_e32 v4, v3
	s_nop 1
	v_permlane32_swap_b32_e32 v3, v4
	v_add_f32_e32 v3, v3, v4
	v_cndmask_b32_e64 v4, v3, v2, s[4:5]
	v_add_co_u32_e32 v2, vcc, 0x62d00000, v104
	s_nop 1
	v_addc_co_u32_e32 v3, vcc, 0, v105, vcc
	global_store_dword v[2:3], v4, off
	s_cbranch_scc1 .LBB0_2571
	s_waitcnt vmcnt(5)
	v_mfma_f32_32x32x16_bf16 v[2:17], v[42:45], v[94:97], 0
	s_min_i32 s6, s2, s3
	s_ashr_i32 s7, s6, 31
	s_lshl_b64 s[6:7], s[6:7], 12
	v_lshl_add_u64 v[18:19], v[98:99], 0, s[6:7]
	global_load_dwordx4 v[66:69], v[18:19], off
	global_load_dwordx4 v[70:73], v[18:19], off offset:1024
	global_load_dwordx4 v[74:77], v[18:19], off offset:2048
	global_load_dwordx4 v[78:81], v[18:19], off offset:3072
	s_waitcnt vmcnt(8)
	v_mfma_f32_32x32x16_bf16 v[2:17], v[62:65], v[90:93], v[2:17]
	s_waitcnt vmcnt(7)
	v_mfma_f32_32x32x16_bf16 v[2:17], v[34:37], v[86:89], v[2:17]
	s_waitcnt vmcnt(6)
	v_mfma_f32_32x32x16_bf16 v[2:17], v[38:41], v[82:85], v[2:17]
	v_mfma_f32_32x32x16_bf16 v[18:33], v[54:57], v[94:97], 0
	s_nop 10
	v_max_f32_e32 v10, 0, v10
	v_max_f32_e32 v2, 0, v2
	v_mfma_f32_32x32x16_bf16 v[18:33], v[46:49], v[90:93], v[18:33]
	v_max_f32_e32 v11, 0, v11
	v_fma_f32 v10, v10, v116, 0
	v_max_f32_e32 v3, 0, v3
	v_max_f32_e32 v12, 0, v12
	v_fma_f32 v2, v2, v108, 0
	v_fmac_f32_e32 v10, v11, v117
	v_max_f32_e32 v4, 0, v4
	v_max_f32_e32 v13, 0, v13
	v_fmac_f32_e32 v2, v3, v109
	v_fmac_f32_e32 v10, v12, v118
	v_max_f32_e32 v3, 0, v14
	v_max_f32_e32 v5, 0, v5
	v_fmac_f32_e32 v2, v4, v110
	v_fmac_f32_e32 v10, v13, v119
	v_max_f32_e32 v6, 0, v6
	v_fmac_f32_e32 v2, v5, v111
	v_fmac_f32_e32 v10, v3, v120
	v_max_f32_e32 v3, 0, v7
	v_fmac_f32_e32 v2, v6, v112
	v_fmac_f32_e32 v2, v3, v113
	v_max_f32_e32 v3, 0, v15
	v_mfma_f32_32x32x16_bf16 v[18:33], v[50:53], v[86:89], v[18:33]
	v_fmac_f32_e32 v10, v3, v121
	v_max_f32_e32 v3, 0, v8
	v_fmac_f32_e32 v2, v3, v114
	v_max_f32_e32 v3, 0, v16
	v_fmac_f32_e32 v10, v3, v122
	v_max_f32_e32 v3, 0, v9
	v_fmac_f32_e32 v2, v3, v115
	v_max_f32_e32 v3, 0, v17
	v_mfma_f32_32x32x16_bf16 v[18:33], v[58:61], v[82:85], v[18:33]
	v_fmac_f32_e32 v10, v3, v123
	v_mov_b32_e32 v3, v2
	s_nop 1
	v_permlane32_swap_b32_e32 v2, v3
	v_add_f32_e32 v2, v2, v3
	v_mov_b32_e32 v3, v10
	s_nop 1
	v_permlane32_swap_b32_e32 v10, v3
	v_add_f32_e32 v3, v10, v3
	v_cndmask_b32_e64 v2, v3, v2, s[4:5]
	global_store_dword v[106:107], v2, off offset:128
	v_max_f32_e32 v2, 0, v18
	v_max_f32_e32 v4, 0, v19
	v_fma_f32 v2, v2, v124, 0
	v_max_f32_e32 v3, 0, v26
	v_fmac_f32_e32 v2, v4, v125
	v_max_f32_e32 v4, 0, v27
	v_fma_f32 v3, v3, v132, 0
	v_fmac_f32_e32 v3, v4, v133
	v_max_f32_e32 v4, 0, v20
	v_fmac_f32_e32 v2, v4, v126
	v_max_f32_e32 v4, 0, v28
	v_fmac_f32_e32 v3, v4, v134
	v_max_f32_e32 v4, 0, v21
	v_fmac_f32_e32 v2, v4, v127
	v_max_f32_e32 v4, 0, v29
	v_fmac_f32_e32 v3, v4, v135
	v_max_f32_e32 v4, 0, v22
	v_fmac_f32_e32 v2, v4, v128
	v_max_f32_e32 v4, 0, v30
	v_fmac_f32_e32 v3, v4, v136
	v_max_f32_e32 v4, 0, v23
	v_fmac_f32_e32 v2, v4, v129
	v_max_f32_e32 v4, 0, v31
	v_fmac_f32_e32 v3, v4, v137
	v_max_f32_e32 v4, 0, v24
	v_fmac_f32_e32 v2, v4, v130
	v_max_f32_e32 v4, 0, v32
	v_fmac_f32_e32 v3, v4, v138
	v_max_f32_e32 v4, 0, v25
	v_fmac_f32_e32 v2, v4, v131
	v_max_f32_e32 v4, 0, v33
	v_fmac_f32_e32 v3, v4, v139
	v_mov_b32_e32 v4, v2
	s_nop 1
	v_permlane32_swap_b32_e32 v2, v4
	v_add_f32_e32 v2, v2, v4
	v_mov_b32_e32 v4, v3
	s_nop 1
	v_permlane32_swap_b32_e32 v3, v4
	v_add_f32_e32 v3, v3, v4
	v_cndmask_b32_e64 v4, v3, v2, s[4:5]
	v_add_co_u32_e32 v2, vcc, s52, v104
	s_nop 1
	v_addc_co_u32_e32 v3, vcc, 0, v105, vcc
	global_store_dword v[2:3], v4, off offset:128
	s_branch .LBB0_2571
